# weight transposes: loads of three items ahead in flight (four register sets)
# speedup vs baseline: 1.0163x; 1.0029x over previous
.Lptr_dec3_done:
	v_mul_lo_u32 v123, v112, s76
	v_add_u32_e32 v118, v123, v113
	s_lshl_b32 vcc_lo, s76, 5
	v_add_u32_e32 v119, vcc_lo, v118
	v_add_u32_e32 v120, vcc_lo, v119
	v_add_u32_e32 v121, vcc_lo, v120
	global_load_dwordx4 v[72:75], v118, s[30:31]
	global_load_dwordx4 v[76:79], v119, s[30:31]
	global_load_dwordx4 v[80:83], v120, s[30:31]
	global_load_dwordx4 v[84:87], v121, s[30:31]
	s_mul_i32 s48, s81, 3
	s_add_u32 s48, s48, s39
	s_min_u32 s48, s48, s84
	s_sub_u32 s0, s48, 0x80
	s_cmpk_lt_u32 s0, 0x80
	s_cbranch_scc1 .Lptr_dec4_br
	s_cmpk_lt_u32 s0, 0x100
	s_cbranch_scc1 .Lptr_dec4_out
	s_cmpk_lt_u32 s0, 0x3c0
	s_cbranch_scc1 .Lptr_dec4_up
	s_sub_u32 s0, s0, 0x3c0
	s_lshr_b32 s2, s0, 4
	s_and_b32 s3, s0, 15
	s_lshl_b32 s12, s2, 19
	s_lshl_b32 s13, s3, 8
	s_add_u32 s12, s12, s13
	s_add_u32 s30, s21, s12
	s_addc_u32 s31, s68, 0
	s_mul_i32 s12, s3, 0x58000
	s_lshl_b32 s13, s2, 8
	s_add_u32 s12, s12, s13
	s_add_u32 s74, s6, s12
	s_addc_u32 s75, s7, 0
	s_movk_i32 s76, 0x1000
	s_movk_i32 s86, 0x1600
	s_branch .Lptr_dec4_done

.Lptr_dec4_done:
	v_mul_lo_u32 v123, v112, s76
	v_add_u32_e32 v118, v123, v113
	s_lshl_b32 vcc_lo, s76, 5
	v_add_u32_e32 v119, vcc_lo, v118
	v_add_u32_e32 v120, vcc_lo, v119
	v_add_u32_e32 v121, vcc_lo, v120
	global_load_dwordx4 v[124:127], v118, s[30:31]
	global_load_dwordx4 v[128:131], v119, s[30:31]
	global_load_dwordx4 v[132:135], v120, s[30:31]
	global_load_dwordx4 v[136:139], v121, s[30:31]
	s_waitcnt vmcnt(12)
	ds_write_b32 v114, v40 offset:0
	ds_write_b32 v114, v41 offset:4
	ds_write_b32 v114, v42 offset:8
	ds_write_b32 v114, v43 offset:12
	ds_write_b32 v114, v44 offset:8320
	ds_write_b32 v114, v45 offset:8324
	ds_write_b32 v114, v46 offset:8328
	ds_write_b32 v114, v47 offset:8332
	ds_write_b32 v114, v48 offset:16640
	ds_write_b32 v114, v49 offset:16644
	ds_write_b32 v114, v50 offset:16648
	ds_write_b32 v114, v51 offset:16652
	ds_write_b32 v114, v52 offset:24960
	ds_write_b32 v114, v53 offset:24964
	ds_write_b32 v114, v54 offset:24968
	ds_write_b32 v114, v55 offset:24972
	s_waitcnt lgkmcnt(0)
	s_barrier
	ds_read_b32 v88, v115 offset:0
	ds_read_b32 v89, v115 offset:260
	ds_read_b32 v90, v115 offset:520
	ds_read_b32 v91, v115 offset:780
	ds_read_b32 v92, v115 offset:1040
	ds_read_b32 v93, v115 offset:1300
	ds_read_b32 v94, v115 offset:1560
	ds_read_b32 v95, v115 offset:1820
	ds_read_b32 v96, v115 offset:2080
	ds_read_b32 v97, v115 offset:2340
	ds_read_b32 v98, v115 offset:2600
	ds_read_b32 v99, v115 offset:2860
	ds_read_b32 v100, v115 offset:3120
	ds_read_b32 v101, v115 offset:3380
	ds_read_b32 v102, v115 offset:3640
	ds_read_b32 v103, v115 offset:3900
	s_mul_i32 s48, s81, 0
	s_add_u32 s48, s48, s39
	s_min_u32 s48, s48, s84
	s_sub_u32 s0, s48, 0x80
	s_cmpk_lt_u32 s0, 0x80
	s_cbranch_scc1 .Lptr_dec5_br
	s_cmpk_lt_u32 s0, 0x100
	s_cbranch_scc1 .Lptr_dec5_out
	s_cmpk_lt_u32 s0, 0x3c0
	s_cbranch_scc1 .Lptr_dec5_up
	s_sub_u32 s0, s0, 0x3c0
	s_lshr_b32 s2, s0, 4
	s_and_b32 s3, s0, 15
	s_lshl_b32 s12, s2, 19
	s_lshl_b32 s13, s3, 8
	s_add_u32 s12, s12, s13
	s_add_u32 s30, s21, s12
	s_addc_u32 s31, s68, 0
	s_mul_i32 s12, s3, 0x58000
	s_lshl_b32 s13, s2, 8
	s_add_u32 s12, s12, s13
	s_add_u32 s74, s6, s12
	s_addc_u32 s75, s7, 0
	s_movk_i32 s76, 0x1000
	s_movk_i32 s86, 0x1600
	s_branch .Lptr_dec5_done

.Lptr_dec6_done:
	v_mul_lo_u32 v123, v112, s76
	v_add_u32_e32 v118, v123, v113
	s_lshl_b32 vcc_lo, s76, 5
	v_add_u32_e32 v119, vcc_lo, v118
	v_add_u32_e32 v120, vcc_lo, v119
	v_add_u32_e32 v121, vcc_lo, v120
	global_load_dwordx4 v[40:43], v118, s[30:31]
	global_load_dwordx4 v[44:47], v119, s[30:31]
	global_load_dwordx4 v[48:51], v120, s[30:31]
	global_load_dwordx4 v[52:55], v121, s[30:31]
	s_waitcnt vmcnt(14)
	ds_write_b32 v114, v56 offset:33792
	ds_write_b32 v114, v57 offset:33796
	ds_write_b32 v114, v58 offset:33800
	ds_write_b32 v114, v59 offset:33804
	ds_write_b32 v114, v60 offset:42112
	ds_write_b32 v114, v61 offset:42116
	ds_write_b32 v114, v62 offset:42120
	ds_write_b32 v114, v63 offset:42124
	ds_write_b32 v114, v64 offset:50432
	ds_write_b32 v114, v65 offset:50436
	ds_write_b32 v114, v66 offset:50440
	ds_write_b32 v114, v67 offset:50444
	ds_write_b32 v114, v68 offset:58752
	ds_write_b32 v114, v69 offset:58756
	ds_write_b32 v114, v70 offset:58760
	ds_write_b32 v114, v71 offset:58764
	s_waitcnt lgkmcnt(0)
	s_barrier
	ds_read_b32 v88, v115 offset:33792
	ds_read_b32 v89, v115 offset:34052
	ds_read_b32 v90, v115 offset:34312
	ds_read_b32 v91, v115 offset:34572
	ds_read_b32 v92, v115 offset:34832
	ds_read_b32 v93, v115 offset:35092
	ds_read_b32 v94, v115 offset:35352
	ds_read_b32 v95, v115 offset:35612
	ds_read_b32 v96, v115 offset:35872
	ds_read_b32 v97, v115 offset:36132
	ds_read_b32 v98, v115 offset:36392
	ds_read_b32 v99, v115 offset:36652
	ds_read_b32 v100, v115 offset:36912
	ds_read_b32 v101, v115 offset:37172
	ds_read_b32 v102, v115 offset:37432
	ds_read_b32 v103, v115 offset:37692
	s_mul_i32 s48, s81, 1
	s_add_u32 s48, s48, s39
	s_min_u32 s48, s48, s84
	s_sub_u32 s0, s48, 0x80
	s_cmpk_lt_u32 s0, 0x80
	s_cbranch_scc1 .Lptr_dec7_br
	s_cmpk_lt_u32 s0, 0x100
	s_cbranch_scc1 .Lptr_dec7_out
	s_cmpk_lt_u32 s0, 0x3c0
	s_cbranch_scc1 .Lptr_dec7_up
	s_sub_u32 s0, s0, 0x3c0
	s_lshr_b32 s2, s0, 4
	s_and_b32 s3, s0, 15
	s_lshl_b32 s12, s2, 19
	s_lshl_b32 s13, s3, 8
	s_add_u32 s12, s12, s13
	s_add_u32 s30, s21, s12
	s_addc_u32 s31, s68, 0
	s_mul_i32 s12, s3, 0x58000
	s_lshl_b32 s13, s2, 8
	s_add_u32 s12, s12, s13
	s_add_u32 s74, s6, s12
	s_addc_u32 s75, s7, 0
	s_movk_i32 s76, 0x1000
	s_movk_i32 s86, 0x1600
	s_branch .Lptr_dec7_done

.Lptr_dec8_done:
	v_mul_lo_u32 v123, v112, s76
	v_add_u32_e32 v118, v123, v113
	s_lshl_b32 vcc_lo, s76, 5
	v_add_u32_e32 v119, vcc_lo, v118
	v_add_u32_e32 v120, vcc_lo, v119
	v_add_u32_e32 v121, vcc_lo, v120
	global_load_dwordx4 v[56:59], v118, s[30:31]
	global_load_dwordx4 v[60:63], v119, s[30:31]
	global_load_dwordx4 v[64:67], v120, s[30:31]
	global_load_dwordx4 v[68:71], v121, s[30:31]
	s_waitcnt vmcnt(16)
	ds_write_b32 v114, v72 offset:0
	ds_write_b32 v114, v73 offset:4
	ds_write_b32 v114, v74 offset:8
	ds_write_b32 v114, v75 offset:12
	ds_write_b32 v114, v76 offset:8320
	ds_write_b32 v114, v77 offset:8324
	ds_write_b32 v114, v78 offset:8328
	ds_write_b32 v114, v79 offset:8332
	ds_write_b32 v114, v80 offset:16640
	ds_write_b32 v114, v81 offset:16644
	ds_write_b32 v114, v82 offset:16648
	ds_write_b32 v114, v83 offset:16652
	ds_write_b32 v114, v84 offset:24960
	ds_write_b32 v114, v85 offset:24964
	ds_write_b32 v114, v86 offset:24968
	ds_write_b32 v114, v87 offset:24972
	s_waitcnt lgkmcnt(0)
	s_barrier
	ds_read_b32 v88, v115 offset:0
	ds_read_b32 v89, v115 offset:260
	ds_read_b32 v90, v115 offset:520
	ds_read_b32 v91, v115 offset:780
	ds_read_b32 v92, v115 offset:1040
	ds_read_b32 v93, v115 offset:1300
	ds_read_b32 v94, v115 offset:1560
	ds_read_b32 v95, v115 offset:1820
	ds_read_b32 v96, v115 offset:2080
	ds_read_b32 v97, v115 offset:2340
	ds_read_b32 v98, v115 offset:2600
	ds_read_b32 v99, v115 offset:2860
	ds_read_b32 v100, v115 offset:3120
	ds_read_b32 v101, v115 offset:3380
	ds_read_b32 v102, v115 offset:3640
	ds_read_b32 v103, v115 offset:3900
	s_mul_i32 s48, s81, 2
	s_add_u32 s48, s48, s39
	s_min_u32 s48, s48, s84
	s_sub_u32 s0, s48, 0x80
	s_cmpk_lt_u32 s0, 0x80
	s_cbranch_scc1 .Lptr_dec9_br
	s_cmpk_lt_u32 s0, 0x100
	s_cbranch_scc1 .Lptr_dec9_out
	s_cmpk_lt_u32 s0, 0x3c0
	s_cbranch_scc1 .Lptr_dec9_up
	s_sub_u32 s0, s0, 0x3c0
	s_lshr_b32 s2, s0, 4
	s_and_b32 s3, s0, 15
	s_lshl_b32 s12, s2, 19
	s_lshl_b32 s13, s3, 8
	s_add_u32 s12, s12, s13
	s_add_u32 s30, s21, s12
	s_addc_u32 s31, s68, 0
	s_mul_i32 s12, s3, 0x58000
	s_lshl_b32 s13, s2, 8
	s_add_u32 s12, s12, s13
	s_add_u32 s74, s6, s12
	s_addc_u32 s75, s7, 0
	s_movk_i32 s76, 0x1000
	s_movk_i32 s86, 0x1600
	s_branch .Lptr_dec9_done

.Lptr_dec10_done:
	v_mul_lo_u32 v123, v112, s76
	v_add_u32_e32 v118, v123, v113
	s_lshl_b32 vcc_lo, s76, 5
	v_add_u32_e32 v119, vcc_lo, v118
	v_add_u32_e32 v120, vcc_lo, v119
	v_add_u32_e32 v121, vcc_lo, v120
	global_load_dwordx4 v[72:75], v118, s[30:31]
	global_load_dwordx4 v[76:79], v119, s[30:31]
	global_load_dwordx4 v[80:83], v120, s[30:31]
	global_load_dwordx4 v[84:87], v121, s[30:31]
	s_waitcnt vmcnt(18)
	ds_write_b32 v114, v124 offset:33792
	ds_write_b32 v114, v125 offset:33796
	ds_write_b32 v114, v126 offset:33800
	ds_write_b32 v114, v127 offset:33804
	ds_write_b32 v114, v128 offset:42112
	ds_write_b32 v114, v129 offset:42116
	ds_write_b32 v114, v130 offset:42120
	ds_write_b32 v114, v131 offset:42124
	ds_write_b32 v114, v132 offset:50432
	ds_write_b32 v114, v133 offset:50436
	ds_write_b32 v114, v134 offset:50440
	ds_write_b32 v114, v135 offset:50444
	ds_write_b32 v114, v136 offset:58752
	ds_write_b32 v114, v137 offset:58756
	ds_write_b32 v114, v138 offset:58760
	ds_write_b32 v114, v139 offset:58764
	s_waitcnt lgkmcnt(0)
	s_barrier
	ds_read_b32 v88, v115 offset:33792
	ds_read_b32 v89, v115 offset:34052
	ds_read_b32 v90, v115 offset:34312
	ds_read_b32 v91, v115 offset:34572
	ds_read_b32 v92, v115 offset:34832
	ds_read_b32 v93, v115 offset:35092
	ds_read_b32 v94, v115 offset:35352
	ds_read_b32 v95, v115 offset:35612
	ds_read_b32 v96, v115 offset:35872
	ds_read_b32 v97, v115 offset:36132
	ds_read_b32 v98, v115 offset:36392
	ds_read_b32 v99, v115 offset:36652
	ds_read_b32 v100, v115 offset:36912
	ds_read_b32 v101, v115 offset:37172
	ds_read_b32 v102, v115 offset:37432
	ds_read_b32 v103, v115 offset:37692
	s_mul_i32 s48, s81, 3
	s_add_u32 s48, s48, s39
	s_min_u32 s48, s48, s84
	s_sub_u32 s0, s48, 0x80
	s_cmpk_lt_u32 s0, 0x80
	s_cbranch_scc1 .Lptr_dec11_br
	s_cmpk_lt_u32 s0, 0x100
	s_cbranch_scc1 .Lptr_dec11_out
	s_cmpk_lt_u32 s0, 0x3c0
	s_cbranch_scc1 .Lptr_dec11_up
	s_sub_u32 s0, s0, 0x3c0
	s_lshr_b32 s2, s0, 4
	s_and_b32 s3, s0, 15
	s_lshl_b32 s12, s2, 19
	s_lshl_b32 s13, s3, 8
	s_add_u32 s12, s12, s13
	s_add_u32 s30, s21, s12
	s_addc_u32 s31, s68, 0
	s_mul_i32 s12, s3, 0x58000
	s_lshl_b32 s13, s2, 8
	s_add_u32 s12, s12, s13
	s_add_u32 s74, s6, s12
	s_addc_u32 s75, s7, 0
	s_movk_i32 s76, 0x1000
	s_movk_i32 s86, 0x1600
	s_branch .Lptr_dec11_done

.Lptr_dec11_done:
	v_mul_lo_u32 v122, v116, s86
	v_add_u32_e32 v122, v122, v117
	s_waitcnt lgkmcnt(0)
	v_cvt_pk_bf16_f32 v104, v88, v89
	v_cvt_pk_bf16_f32 v105, v90, v91
	v_cvt_pk_bf16_f32 v106, v92, v93
	v_cvt_pk_bf16_f32 v107, v94, v95
	v_cvt_pk_bf16_f32 v108, v96, v97
	v_cvt_pk_bf16_f32 v109, v98, v99
	v_cvt_pk_bf16_f32 v110, v100, v101
	v_cvt_pk_bf16_f32 v111, v102, v103
	global_store_dwordx4 v122, v[104:107], s[74:75]
	global_store_dwordx4 v122, v[108:111], s[74:75] offset:16
	s_nop 1
	s_waitcnt vmcnt(14)
	ds_write_b32 v114, v40 offset:0
	ds_write_b32 v114, v41 offset:4
	ds_write_b32 v114, v42 offset:8
	ds_write_b32 v114, v43 offset:12
	ds_write_b32 v114, v44 offset:8320
	ds_write_b32 v114, v45 offset:8324
	ds_write_b32 v114, v46 offset:8328
	ds_write_b32 v114, v47 offset:8332
	ds_write_b32 v114, v48 offset:16640
	ds_write_b32 v114, v49 offset:16644
	ds_write_b32 v114, v50 offset:16648
	ds_write_b32 v114, v51 offset:16652
	ds_write_b32 v114, v52 offset:24960
	ds_write_b32 v114, v53 offset:24964
	ds_write_b32 v114, v54 offset:24968
	ds_write_b32 v114, v55 offset:24972
	s_waitcnt lgkmcnt(0)
	s_barrier
	ds_read_b32 v88, v115 offset:0
	ds_read_b32 v89, v115 offset:260
	ds_read_b32 v90, v115 offset:520
	ds_read_b32 v91, v115 offset:780
	ds_read_b32 v92, v115 offset:1040
	ds_read_b32 v93, v115 offset:1300
	ds_read_b32 v94, v115 offset:1560
	ds_read_b32 v95, v115 offset:1820
	ds_read_b32 v96, v115 offset:2080
	ds_read_b32 v97, v115 offset:2340
	ds_read_b32 v98, v115 offset:2600
	ds_read_b32 v99, v115 offset:2860
	ds_read_b32 v100, v115 offset:3120
	ds_read_b32 v101, v115 offset:3380
	ds_read_b32 v102, v115 offset:3640
	ds_read_b32 v103, v115 offset:3900
	s_mul_i32 s48, s81, 4
	s_add_u32 s48, s48, s39
	s_min_u32 s48, s48, s84
	s_sub_u32 s0, s48, 0x80
	s_cmpk_lt_u32 s0, 0x80
	s_cbranch_scc1 .Lptr_dec12_br
	s_cmpk_lt_u32 s0, 0x100
	s_cbranch_scc1 .Lptr_dec12_out
	s_cmpk_lt_u32 s0, 0x3c0
	s_cbranch_scc1 .Lptr_dec12_up
	s_sub_u32 s0, s0, 0x3c0
	s_lshr_b32 s2, s0, 4
	s_and_b32 s3, s0, 15
	s_lshl_b32 s12, s2, 19
	s_lshl_b32 s13, s3, 8
	s_add_u32 s12, s12, s13
	s_add_u32 s30, s21, s12
	s_addc_u32 s31, s68, 0
	s_mul_i32 s12, s3, 0x58000
	s_lshl_b32 s13, s2, 8
	s_add_u32 s12, s12, s13
	s_add_u32 s74, s6, s12
	s_addc_u32 s75, s7, 0
	s_movk_i32 s76, 0x1000
	s_movk_i32 s86, 0x1600
	s_branch .Lptr_dec12_done

.Lptr_dec12_done:
	v_mul_lo_u32 v122, v116, s86
	v_add_u32_e32 v122, v122, v117
	s_waitcnt lgkmcnt(0)
	v_cvt_pk_bf16_f32 v104, v88, v89
	v_cvt_pk_bf16_f32 v105, v90, v91
	v_cvt_pk_bf16_f32 v106, v92, v93
	v_cvt_pk_bf16_f32 v107, v94, v95
	v_cvt_pk_bf16_f32 v108, v96, v97
	v_cvt_pk_bf16_f32 v109, v98, v99
	v_cvt_pk_bf16_f32 v110, v100, v101
	v_cvt_pk_bf16_f32 v111, v102, v103
	global_store_dwordx4 v122, v[104:107], s[74:75]
	global_store_dwordx4 v122, v[108:111], s[74:75] offset:16
	s_nop 1
	s_waitcnt vmcnt(10)
	ds_write_b32 v114, v56 offset:33792
	ds_write_b32 v114, v57 offset:33796
	ds_write_b32 v114, v58 offset:33800
	ds_write_b32 v114, v59 offset:33804
	ds_write_b32 v114, v60 offset:42112
	ds_write_b32 v114, v61 offset:42116
	ds_write_b32 v114, v62 offset:42120
	ds_write_b32 v114, v63 offset:42124
	ds_write_b32 v114, v64 offset:50432
	ds_write_b32 v114, v65 offset:50436
	ds_write_b32 v114, v66 offset:50440
	ds_write_b32 v114, v67 offset:50444
	ds_write_b32 v114, v68 offset:58752
	ds_write_b32 v114, v69 offset:58756
	ds_write_b32 v114, v70 offset:58760
	ds_write_b32 v114, v71 offset:58764
	s_waitcnt lgkmcnt(0)
	s_barrier
	ds_read_b32 v88, v115 offset:33792
	ds_read_b32 v89, v115 offset:34052
	ds_read_b32 v90, v115 offset:34312
	ds_read_b32 v91, v115 offset:34572
	ds_read_b32 v92, v115 offset:34832
	ds_read_b32 v93, v115 offset:35092
	ds_read_b32 v94, v115 offset:35352
	ds_read_b32 v95, v115 offset:35612
	ds_read_b32 v96, v115 offset:35872
	ds_read_b32 v97, v115 offset:36132
	ds_read_b32 v98, v115 offset:36392
	ds_read_b32 v99, v115 offset:36652
	ds_read_b32 v100, v115 offset:36912
	ds_read_b32 v101, v115 offset:37172
	ds_read_b32 v102, v115 offset:37432
	ds_read_b32 v103, v115 offset:37692
	s_mul_i32 s48, s81, 5
	s_add_u32 s48, s48, s39
	s_min_u32 s48, s48, s84
	s_sub_u32 s0, s48, 0x80
	s_cmpk_lt_u32 s0, 0x80
	s_cbranch_scc1 .Lptr_dec13_br
	s_cmpk_lt_u32 s0, 0x100
	s_cbranch_scc1 .Lptr_dec13_out
	s_cmpk_lt_u32 s0, 0x3c0
	s_cbranch_scc1 .Lptr_dec13_up
	s_sub_u32 s0, s0, 0x3c0
	s_lshr_b32 s2, s0, 4
	s_and_b32 s3, s0, 15
	s_lshl_b32 s12, s2, 19
	s_lshl_b32 s13, s3, 8
	s_add_u32 s12, s12, s13
	s_add_u32 s30, s21, s12
	s_addc_u32 s31, s68, 0
	s_mul_i32 s12, s3, 0x58000
	s_lshl_b32 s13, s2, 8
	s_add_u32 s12, s12, s13
	s_add_u32 s74, s6, s12
	s_addc_u32 s75, s7, 0
	s_movk_i32 s76, 0x1000
	s_movk_i32 s86, 0x1600
	s_branch .Lptr_dec13_done

.Lptr_dec13_done:
	v_mul_lo_u32 v122, v116, s86
	v_add_u32_e32 v122, v122, v117
	s_waitcnt lgkmcnt(0)
	v_cvt_pk_bf16_f32 v104, v88, v89
	v_cvt_pk_bf16_f32 v105, v90, v91
	v_cvt_pk_bf16_f32 v106, v92, v93
	v_cvt_pk_bf16_f32 v107, v94, v95
	v_cvt_pk_bf16_f32 v108, v96, v97
	v_cvt_pk_bf16_f32 v109, v98, v99
	v_cvt_pk_bf16_f32 v110, v100, v101
	v_cvt_pk_bf16_f32 v111, v102, v103
	global_store_dwordx4 v122, v[104:107], s[74:75]
	global_store_dwordx4 v122, v[108:111], s[74:75] offset:16
	s_nop 1
	s_waitcnt vmcnt(6)
	ds_write_b32 v114, v72 offset:0
	ds_write_b32 v114, v73 offset:4
	ds_write_b32 v114, v74 offset:8
	ds_write_b32 v114, v75 offset:12
	ds_write_b32 v114, v76 offset:8320
	ds_write_b32 v114, v77 offset:8324
	ds_write_b32 v114, v78 offset:8328
	ds_write_b32 v114, v79 offset:8332
	ds_write_b32 v114, v80 offset:16640
	ds_write_b32 v114, v81 offset:16644
	ds_write_b32 v114, v82 offset:16648
	ds_write_b32 v114, v83 offset:16652
	ds_write_b32 v114, v84 offset:24960
	ds_write_b32 v114, v85 offset:24964
	ds_write_b32 v114, v86 offset:24968
	ds_write_b32 v114, v87 offset:24972
	s_waitcnt lgkmcnt(0)
	s_barrier
	ds_read_b32 v88, v115 offset:0
	ds_read_b32 v89, v115 offset:260
	ds_read_b32 v90, v115 offset:520
	ds_read_b32 v91, v115 offset:780
	ds_read_b32 v92, v115 offset:1040
	ds_read_b32 v93, v115 offset:1300
	ds_read_b32 v94, v115 offset:1560
	ds_read_b32 v95, v115 offset:1820
	ds_read_b32 v96, v115 offset:2080
	ds_read_b32 v97, v115 offset:2340
	ds_read_b32 v98, v115 offset:2600
	ds_read_b32 v99, v115 offset:2860
	ds_read_b32 v100, v115 offset:3120
	ds_read_b32 v101, v115 offset:3380
	ds_read_b32 v102, v115 offset:3640
	ds_read_b32 v103, v115 offset:3900
	s_mul_i32 s48, s81, 6
	s_add_u32 s48, s48, s39
	s_min_u32 s48, s48, s84
	s_sub_u32 s0, s48, 0x80
	s_cmpk_lt_u32 s0, 0x80
	s_cbranch_scc1 .Lptr_dec14_br
	s_cmpk_lt_u32 s0, 0x100
	s_cbranch_scc1 .Lptr_dec14_out
	s_cmpk_lt_u32 s0, 0x3c0
	s_cbranch_scc1 .Lptr_dec14_up
	s_sub_u32 s0, s0, 0x3c0
	s_lshr_b32 s2, s0, 4
	s_and_b32 s3, s0, 15
	s_lshl_b32 s12, s2, 19
	s_lshl_b32 s13, s3, 8
	s_add_u32 s12, s12, s13
	s_add_u32 s30, s21, s12
	s_addc_u32 s31, s68, 0
	s_mul_i32 s12, s3, 0x58000
	s_lshl_b32 s13, s2, 8
	s_add_u32 s12, s12, s13
	s_add_u32 s74, s6, s12
	s_addc_u32 s75, s7, 0
	s_movk_i32 s76, 0x1000
	s_movk_i32 s86, 0x1600
	s_branch .Lptr_dec14_done

.Lp0t_kdone:
	v_lshrrev_b32_e32 v112, 4, v1
	v_and_b32_e32 v113, 15, v1
	v_lshlrev_b32_e32 v113, 4, v113
	v_mul_u32_u24_e32 v114, 0x104, v112
	v_add_u32_e32 v114, v114, v113
	v_lshrrev_b32_e32 v116, 3, v1
	v_and_b32_e32 v117, 7, v1
	v_mul_u32_u24_e32 v115, 0x1040, v117
	v_lshl_add_u32 v115, v116, 2, v115
	v_lshlrev_b32_e32 v117, 5, v117
	s_mul_i32 s48, s85, 0
	s_add_u32 s48, s48, s86
	s_min_u32 s48, s48, s84
	s_sub_u32 s0, s48, 0xe0
	s_mul_i32 s2, s0, 0x4ed
	s_lshr_b32 s2, s2, 17
	s_mul_i32 s3, s2, 0x68
	s_sub_u32 s3, s0, s3
	s_mul_i32 s4, s2, 0x340000
	s_lshl_b32 s0, s3, 8
	s_add_u32 s4, s4, s0
	s_add_u32 s6, s80, s4
	s_addc_u32 s7, s81, 0
	s_lshl_b32 s4, s3, 17
	s_lshl_b32 s0, s2, 8
	s_add_u32 s4, s4, s0
	s_add_u32 s8, s82, s4
	s_addc_u32 s9, s83, 0
	s_movk_i32 s10, 0x6800
	s_movk_i32 s11, 0x800
	v_mul_lo_u32 v123, v112, s10
	v_add_u32_e32 v118, v123, v113
	s_lshl_b32 vcc_lo, s10, 5
	v_add_u32_e32 v119, vcc_lo, v118
	v_add_u32_e32 v120, vcc_lo, v119
	v_add_u32_e32 v121, vcc_lo, v120
	global_load_dwordx4 v[40:43], v118, s[6:7]
	global_load_dwordx4 v[44:47], v119, s[6:7]
	global_load_dwordx4 v[48:51], v120, s[6:7]
	global_load_dwordx4 v[52:55], v121, s[6:7]
	s_mul_i32 s48, s85, 1
	s_add_u32 s48, s48, s86
	s_min_u32 s48, s48, s84
	s_sub_u32 s0, s48, 0xe0
	s_mul_i32 s2, s0, 0x4ed
	s_lshr_b32 s2, s2, 17
	s_mul_i32 s3, s2, 0x68
	s_sub_u32 s3, s0, s3
	s_mul_i32 s4, s2, 0x340000
	s_lshl_b32 s0, s3, 8
	s_add_u32 s4, s4, s0
	s_add_u32 s6, s80, s4
	s_addc_u32 s7, s81, 0
	s_lshl_b32 s4, s3, 17
	s_lshl_b32 s0, s2, 8
	s_add_u32 s4, s4, s0
	s_add_u32 s8, s82, s4
	s_addc_u32 s9, s83, 0
	s_movk_i32 s10, 0x6800
	s_movk_i32 s11, 0x800
	v_mul_lo_u32 v123, v112, s10
	v_add_u32_e32 v118, v123, v113
	s_lshl_b32 vcc_lo, s10, 5
	v_add_u32_e32 v119, vcc_lo, v118
	v_add_u32_e32 v120, vcc_lo, v119
	v_add_u32_e32 v121, vcc_lo, v120
	global_load_dwordx4 v[56:59], v118, s[6:7]
	global_load_dwordx4 v[60:63], v119, s[6:7]
	global_load_dwordx4 v[64:67], v120, s[6:7]
	global_load_dwordx4 v[68:71], v121, s[6:7]
	s_mul_i32 s48, s85, 2
	s_add_u32 s48, s48, s86
	s_min_u32 s48, s48, s84
	s_sub_u32 s0, s48, 0xe0
	s_mul_i32 s2, s0, 0x4ed
	s_lshr_b32 s2, s2, 17
	s_mul_i32 s3, s2, 0x68
	s_sub_u32 s3, s0, s3
	s_mul_i32 s4, s2, 0x340000
	s_lshl_b32 s0, s3, 8
	s_add_u32 s4, s4, s0
	s_add_u32 s6, s80, s4
	s_addc_u32 s7, s81, 0
	s_lshl_b32 s4, s3, 17
	s_lshl_b32 s0, s2, 8
	s_add_u32 s4, s4, s0
	s_add_u32 s8, s82, s4
	s_addc_u32 s9, s83, 0
	s_movk_i32 s10, 0x6800
	s_movk_i32 s11, 0x800
	v_mul_lo_u32 v123, v112, s10
	v_add_u32_e32 v118, v123, v113
	s_lshl_b32 vcc_lo, s10, 5
	v_add_u32_e32 v119, vcc_lo, v118
	v_add_u32_e32 v120, vcc_lo, v119
	v_add_u32_e32 v121, vcc_lo, v120
	global_load_dwordx4 v[72:75], v118, s[6:7]
	global_load_dwordx4 v[76:79], v119, s[6:7]
	global_load_dwordx4 v[80:83], v120, s[6:7]
	global_load_dwordx4 v[84:87], v121, s[6:7]
	s_mul_i32 s48, s85, 3
	s_add_u32 s48, s48, s86
	s_min_u32 s48, s48, s84
	s_sub_u32 s0, s48, 0xe0
	s_mul_i32 s2, s0, 0x4ed
	s_lshr_b32 s2, s2, 17
	s_mul_i32 s3, s2, 0x68
	s_sub_u32 s3, s0, s3
	s_mul_i32 s4, s2, 0x340000
	s_lshl_b32 s0, s3, 8
	s_add_u32 s4, s4, s0
	s_add_u32 s6, s80, s4
	s_addc_u32 s7, s81, 0
	s_lshl_b32 s4, s3, 17
	s_lshl_b32 s0, s2, 8
	s_add_u32 s4, s4, s0
	s_add_u32 s8, s82, s4
	s_addc_u32 s9, s83, 0
	s_movk_i32 s10, 0x6800
	s_movk_i32 s11, 0x800
	v_mul_lo_u32 v123, v112, s10
	v_add_u32_e32 v118, v123, v113
	s_lshl_b32 vcc_lo, s10, 5
	v_add_u32_e32 v119, vcc_lo, v118
	v_add_u32_e32 v120, vcc_lo, v119
	v_add_u32_e32 v121, vcc_lo, v120
	global_load_dwordx4 v[124:127], v118, s[6:7]
	global_load_dwordx4 v[128:131], v119, s[6:7]
	global_load_dwordx4 v[132:135], v120, s[6:7]
	global_load_dwordx4 v[136:139], v121, s[6:7]
	s_waitcnt vmcnt(12)
	ds_write_b32 v114, v40 offset:0
	ds_write_b32 v114, v41 offset:4
	ds_write_b32 v114, v42 offset:8
	ds_write_b32 v114, v43 offset:12
	ds_write_b32 v114, v44 offset:8320
	ds_write_b32 v114, v45 offset:8324
	ds_write_b32 v114, v46 offset:8328
	ds_write_b32 v114, v47 offset:8332
	ds_write_b32 v114, v48 offset:16640
	ds_write_b32 v114, v49 offset:16644
	ds_write_b32 v114, v50 offset:16648
	ds_write_b32 v114, v51 offset:16652
	ds_write_b32 v114, v52 offset:24960
	ds_write_b32 v114, v53 offset:24964
	ds_write_b32 v114, v54 offset:24968
	ds_write_b32 v114, v55 offset:24972
	s_waitcnt lgkmcnt(0)
	s_barrier
	ds_read_b32 v88, v115 offset:0
	ds_read_b32 v89, v115 offset:260
	ds_read_b32 v90, v115 offset:520
	ds_read_b32 v91, v115 offset:780
	ds_read_b32 v92, v115 offset:1040
	ds_read_b32 v93, v115 offset:1300
	ds_read_b32 v94, v115 offset:1560
	ds_read_b32 v95, v115 offset:1820
	ds_read_b32 v96, v115 offset:2080
	ds_read_b32 v97, v115 offset:2340
	ds_read_b32 v98, v115 offset:2600
	ds_read_b32 v99, v115 offset:2860
	ds_read_b32 v100, v115 offset:3120
	ds_read_b32 v101, v115 offset:3380
	ds_read_b32 v102, v115 offset:3640
	ds_read_b32 v103, v115 offset:3900
	s_mul_i32 s48, s85, 0
	s_add_u32 s48, s48, s86
	s_min_u32 s48, s48, s84
	s_sub_u32 s0, s48, 0xe0
	s_mul_i32 s2, s0, 0x4ed
	s_lshr_b32 s2, s2, 17
	s_mul_i32 s3, s2, 0x68
	s_sub_u32 s3, s0, s3
	s_mul_i32 s4, s2, 0x340000
	s_lshl_b32 s0, s3, 8
	s_add_u32 s4, s4, s0
	s_add_u32 s6, s80, s4
	s_addc_u32 s7, s81, 0
	s_lshl_b32 s4, s3, 17
	s_lshl_b32 s0, s2, 8
	s_add_u32 s4, s4, s0
	s_add_u32 s8, s82, s4
	s_addc_u32 s9, s83, 0
	s_movk_i32 s10, 0x6800
	s_movk_i32 s11, 0x800
	v_mul_lo_u32 v122, v116, s11
	v_add_u32_e32 v122, v122, v117
	s_waitcnt lgkmcnt(0)
	v_cvt_pk_bf16_f32 v104, v88, v89
	v_cvt_pk_bf16_f32 v105, v90, v91
	v_cvt_pk_bf16_f32 v106, v92, v93
	v_cvt_pk_bf16_f32 v107, v94, v95
	v_cvt_pk_bf16_f32 v108, v96, v97
	v_cvt_pk_bf16_f32 v109, v98, v99
	v_cvt_pk_bf16_f32 v110, v100, v101
	v_cvt_pk_bf16_f32 v111, v102, v103
	global_store_dwordx4 v122, v[104:107], s[8:9]
	global_store_dwordx4 v122, v[108:111], s[8:9] offset:16
	s_nop 1
	s_waitcnt vmcnt(10)
	ds_write_b32 v114, v56 offset:33792
	ds_write_b32 v114, v57 offset:33796
	ds_write_b32 v114, v58 offset:33800
	ds_write_b32 v114, v59 offset:33804
	ds_write_b32 v114, v60 offset:42112
	ds_write_b32 v114, v61 offset:42116
	ds_write_b32 v114, v62 offset:42120
	ds_write_b32 v114, v63 offset:42124
	ds_write_b32 v114, v64 offset:50432
	ds_write_b32 v114, v65 offset:50436
	ds_write_b32 v114, v66 offset:50440
	ds_write_b32 v114, v67 offset:50444
	ds_write_b32 v114, v68 offset:58752
	ds_write_b32 v114, v69 offset:58756
	ds_write_b32 v114, v70 offset:58760
	ds_write_b32 v114, v71 offset:58764
	s_waitcnt lgkmcnt(0)
	s_barrier
	ds_read_b32 v88, v115 offset:33792
	ds_read_b32 v89, v115 offset:34052
	ds_read_b32 v90, v115 offset:34312
	ds_read_b32 v91, v115 offset:34572
	ds_read_b32 v92, v115 offset:34832
	ds_read_b32 v93, v115 offset:35092
	ds_read_b32 v94, v115 offset:35352
	ds_read_b32 v95, v115 offset:35612
	ds_read_b32 v96, v115 offset:35872
	ds_read_b32 v97, v115 offset:36132
	ds_read_b32 v98, v115 offset:36392
	ds_read_b32 v99, v115 offset:36652
	ds_read_b32 v100, v115 offset:36912
	ds_read_b32 v101, v115 offset:37172
	ds_read_b32 v102, v115 offset:37432
	ds_read_b32 v103, v115 offset:37692
	s_mul_i32 s48, s85, 1
	s_add_u32 s48, s48, s86
	s_min_u32 s48, s48, s84
	s_sub_u32 s0, s48, 0xe0
	s_mul_i32 s2, s0, 0x4ed
	s_lshr_b32 s2, s2, 17
	s_mul_i32 s3, s2, 0x68
	s_sub_u32 s3, s0, s3
	s_mul_i32 s4, s2, 0x340000
	s_lshl_b32 s0, s3, 8
	s_add_u32 s4, s4, s0
	s_add_u32 s6, s80, s4
	s_addc_u32 s7, s81, 0
	s_lshl_b32 s4, s3, 17
	s_lshl_b32 s0, s2, 8
	s_add_u32 s4, s4, s0
	s_add_u32 s8, s82, s4
	s_addc_u32 s9, s83, 0
	s_movk_i32 s10, 0x6800
	s_movk_i32 s11, 0x800
	v_mul_lo_u32 v122, v116, s11
	v_add_u32_e32 v122, v122, v117
	s_waitcnt lgkmcnt(0)
	v_cvt_pk_bf16_f32 v104, v88, v89
	v_cvt_pk_bf16_f32 v105, v90, v91
	v_cvt_pk_bf16_f32 v106, v92, v93
	v_cvt_pk_bf16_f32 v107, v94, v95
	v_cvt_pk_bf16_f32 v108, v96, v97
	v_cvt_pk_bf16_f32 v109, v98, v99
	v_cvt_pk_bf16_f32 v110, v100, v101
	v_cvt_pk_bf16_f32 v111, v102, v103
	global_store_dwordx4 v122, v[104:107], s[8:9]
	global_store_dwordx4 v122, v[108:111], s[8:9] offset:16
	s_nop 1
	s_waitcnt vmcnt(8)
	ds_write_b32 v114, v72 offset:0
	ds_write_b32 v114, v73 offset:4
	ds_write_b32 v114, v74 offset:8
	ds_write_b32 v114, v75 offset:12
	ds_write_b32 v114, v76 offset:8320
	ds_write_b32 v114, v77 offset:8324
	ds_write_b32 v114, v78 offset:8328
	ds_write_b32 v114, v79 offset:8332
	ds_write_b32 v114, v80 offset:16640
	ds_write_b32 v114, v81 offset:16644
	ds_write_b32 v114, v82 offset:16648
	ds_write_b32 v114, v83 offset:16652
	ds_write_b32 v114, v84 offset:24960
	ds_write_b32 v114, v85 offset:24964
	ds_write_b32 v114, v86 offset:24968
	ds_write_b32 v114, v87 offset:24972
	s_waitcnt lgkmcnt(0)
	s_barrier
	ds_read_b32 v88, v115 offset:0
	ds_read_b32 v89, v115 offset:260
	ds_read_b32 v90, v115 offset:520
	ds_read_b32 v91, v115 offset:780
	ds_read_b32 v92, v115 offset:1040
	ds_read_b32 v93, v115 offset:1300
	ds_read_b32 v94, v115 offset:1560
	ds_read_b32 v95, v115 offset:1820
	ds_read_b32 v96, v115 offset:2080
	ds_read_b32 v97, v115 offset:2340
	ds_read_b32 v98, v115 offset:2600
	ds_read_b32 v99, v115 offset:2860
	ds_read_b32 v100, v115 offset:3120
	ds_read_b32 v101, v115 offset:3380
	ds_read_b32 v102, v115 offset:3640
	ds_read_b32 v103, v115 offset:3900
	s_mul_i32 s48, s85, 2
	s_add_u32 s48, s48, s86
	s_min_u32 s48, s48, s84
	s_sub_u32 s0, s48, 0xe0
	s_mul_i32 s2, s0, 0x4ed
	s_lshr_b32 s2, s2, 17
	s_mul_i32 s3, s2, 0x68
	s_sub_u32 s3, s0, s3
	s_mul_i32 s4, s2, 0x340000
	s_lshl_b32 s0, s3, 8
	s_add_u32 s4, s4, s0
	s_add_u32 s6, s80, s4
	s_addc_u32 s7, s81, 0
	s_lshl_b32 s4, s3, 17
	s_lshl_b32 s0, s2, 8
	s_add_u32 s4, s4, s0
	s_add_u32 s8, s82, s4
	s_addc_u32 s9, s83, 0
	s_movk_i32 s10, 0x6800
	s_movk_i32 s11, 0x800
	v_mul_lo_u32 v122, v116, s11
	v_add_u32_e32 v122, v122, v117
	s_waitcnt lgkmcnt(0)
	v_cvt_pk_bf16_f32 v104, v88, v89
	v_cvt_pk_bf16_f32 v105, v90, v91
	v_cvt_pk_bf16_f32 v106, v92, v93
	v_cvt_pk_bf16_f32 v107, v94, v95
	v_cvt_pk_bf16_f32 v108, v96, v97
	v_cvt_pk_bf16_f32 v109, v98, v99
	v_cvt_pk_bf16_f32 v110, v100, v101
	v_cvt_pk_bf16_f32 v111, v102, v103
	global_store_dwordx4 v122, v[104:107], s[8:9]
	global_store_dwordx4 v122, v[108:111], s[8:9] offset:16
	s_nop 1
	s_waitcnt vmcnt(6)
	ds_write_b32 v114, v124 offset:33792
	ds_write_b32 v114, v125 offset:33796
	ds_write_b32 v114, v126 offset:33800
	ds_write_b32 v114, v127 offset:33804
	ds_write_b32 v114, v128 offset:42112
	ds_write_b32 v114, v129 offset:42116
	ds_write_b32 v114, v130 offset:42120
	ds_write_b32 v114, v131 offset:42124
	ds_write_b32 v114, v132 offset:50432
	ds_write_b32 v114, v133 offset:50436
	ds_write_b32 v114, v134 offset:50440
	ds_write_b32 v114, v135 offset:50444
	ds_write_b32 v114, v136 offset:58752
	ds_write_b32 v114, v137 offset:58756
	ds_write_b32 v114, v138 offset:58760
	ds_write_b32 v114, v139 offset:58764
	s_waitcnt lgkmcnt(0)
	s_barrier
	ds_read_b32 v88, v115 offset:33792
	ds_read_b32 v89, v115 offset:34052
	ds_read_b32 v90, v115 offset:34312
	ds_read_b32 v91, v115 offset:34572
	ds_read_b32 v92, v115 offset:34832
	ds_read_b32 v93, v115 offset:35092
	ds_read_b32 v94, v115 offset:35352
	ds_read_b32 v95, v115 offset:35612
	ds_read_b32 v96, v115 offset:35872
	ds_read_b32 v97, v115 offset:36132
	ds_read_b32 v98, v115 offset:36392
	ds_read_b32 v99, v115 offset:36652
	ds_read_b32 v100, v115 offset:36912
	ds_read_b32 v101, v115 offset:37172
	ds_read_b32 v102, v115 offset:37432
	ds_read_b32 v103, v115 offset:37692
	s_mul_i32 s48, s85, 3
	s_add_u32 s48, s48, s86
	s_min_u32 s48, s48, s84
	s_sub_u32 s0, s48, 0xe0
	s_mul_i32 s2, s0, 0x4ed
	s_lshr_b32 s2, s2, 17
	s_mul_i32 s3, s2, 0x68
	s_sub_u32 s3, s0, s3
	s_mul_i32 s4, s2, 0x340000
	s_lshl_b32 s0, s3, 8
	s_add_u32 s4, s4, s0
	s_add_u32 s6, s80, s4
	s_addc_u32 s7, s81, 0
	s_lshl_b32 s4, s3, 17
	s_lshl_b32 s0, s2, 8
	s_add_u32 s4, s4, s0
	s_add_u32 s8, s82, s4
	s_addc_u32 s9, s83, 0
	s_movk_i32 s10, 0x6800
	s_movk_i32 s11, 0x800
	v_mul_lo_u32 v122, v116, s11
	v_add_u32_e32 v122, v122, v117
	s_waitcnt lgkmcnt(0)
	v_cvt_pk_bf16_f32 v104, v88, v89
	v_cvt_pk_bf16_f32 v105, v90, v91
	v_cvt_pk_bf16_f32 v106, v92, v93
	v_cvt_pk_bf16_f32 v107, v94, v95
	v_cvt_pk_bf16_f32 v108, v96, v97
	v_cvt_pk_bf16_f32 v109, v98, v99
	v_cvt_pk_bf16_f32 v110, v100, v101
	v_cvt_pk_bf16_f32 v111, v102, v103
	global_store_dwordx4 v122, v[104:107], s[8:9]
	global_store_dwordx4 v122, v[108:111], s[8:9] offset:16
	s_nop 1
	s_waitcnt vmcnt(0)
	s_barrier
	s_branch .LBB0_726
